# v13 + SCAN phase (ssd chunk-state scan) rewritten as a 6-chunk-deep software pipeline: loads of chunk c+6 in flight while chunk c is stored/updated (was one full memory round trip per chunk)
# baseline (speedup 1.0000x reference)
.LBB0_579:
	v_readlane_b32 s0, v254, 8
	v_readlane_b32 s1, v254, 9
	v_and_b32_e32 v6, 0xffff, v51
	v_lshlrev_b32_e32 v6, 2, v6
	v_lshl_or_b32 v6, v2, 23, v6
	v_add_u32_e32 v7, 0x1000000, v6
	v_add_u32_e32 v8, 0x2000000, v6
	v_add_u32_e32 v9, 0x3000000, v6
	s_nop 1
	s_mov_b64 s[4:5], s[0:1]
	global_load_dword v60, v6, s[0:1]
	global_load_dword v64, v36, s[12:13] offset:0
	global_load_dword v61, v7, s[0:1]
	global_load_dword v65, v34, s[12:13] offset:0
	global_load_dword v62, v8, s[0:1]
	global_load_dword v66, v32, s[12:13] offset:0
	global_load_dword v63, v9, s[0:1]
	global_load_dword v67, v30, s[12:13] offset:0
	s_add_u32 s0, s0, 0x40000
	s_addc_u32 s1, s1, 0
	global_load_dword v68, v6, s[0:1]
	global_load_dword v72, v36, s[12:13] offset:64
	global_load_dword v69, v7, s[0:1]
	global_load_dword v73, v34, s[12:13] offset:64
	global_load_dword v70, v8, s[0:1]
	global_load_dword v74, v32, s[12:13] offset:64
	global_load_dword v71, v9, s[0:1]
	global_load_dword v75, v30, s[12:13] offset:64
	s_add_u32 s0, s0, 0x40000
	s_addc_u32 s1, s1, 0
	global_load_dword v76, v6, s[0:1]
	global_load_dword v80, v36, s[12:13] offset:128
	global_load_dword v77, v7, s[0:1]
	global_load_dword v81, v34, s[12:13] offset:128
	global_load_dword v78, v8, s[0:1]
	global_load_dword v82, v32, s[12:13] offset:128
	global_load_dword v79, v9, s[0:1]
	global_load_dword v83, v30, s[12:13] offset:128
	s_add_u32 s0, s0, 0x40000
	s_addc_u32 s1, s1, 0
	global_load_dword v84, v6, s[0:1]
	global_load_dword v88, v36, s[12:13] offset:192
	global_load_dword v85, v7, s[0:1]
	global_load_dword v89, v34, s[12:13] offset:192
	global_load_dword v86, v8, s[0:1]
	global_load_dword v90, v32, s[12:13] offset:192
	global_load_dword v87, v9, s[0:1]
	global_load_dword v91, v30, s[12:13] offset:192
	s_add_u32 s0, s0, 0x40000
	s_addc_u32 s1, s1, 0
	global_load_dword v92, v6, s[0:1]
	global_load_dword v96, v36, s[12:13] offset:256
	global_load_dword v93, v7, s[0:1]
	global_load_dword v97, v34, s[12:13] offset:256
	global_load_dword v94, v8, s[0:1]
	global_load_dword v98, v32, s[12:13] offset:256
	global_load_dword v95, v9, s[0:1]
	global_load_dword v99, v30, s[12:13] offset:256
	s_add_u32 s0, s0, 0x40000
	s_addc_u32 s1, s1, 0
	global_load_dword v100, v6, s[0:1]
	global_load_dword v104, v36, s[12:13] offset:320
	global_load_dword v101, v7, s[0:1]
	global_load_dword v105, v34, s[12:13] offset:320
	global_load_dword v102, v8, s[0:1]
	global_load_dword v106, v32, s[12:13] offset:320
	global_load_dword v103, v9, s[0:1]
	global_load_dword v107, v30, s[12:13] offset:320
	s_add_u32 s0, s0, 0x40000
	s_addc_u32 s1, s1, 0
	s_waitcnt vmcnt(40)
	v_cvt_pk_bf16_f32 v52, v48, v49
	v_cvt_pk_bf16_f32 v53, v44, v45
	v_cvt_pk_bf16_f32 v54, v46, v47
	v_cvt_pk_bf16_f32 v55, v40, v41
	global_store_dword v6, v52, s[4:5]
	global_store_dword v7, v53, s[4:5]
	global_store_dword v8, v54, s[4:5]
	global_store_dword v9, v55, s[4:5]
	v_lshlrev_b32_e32 v56, 16, v60
	v_and_b32_e32 v57, 0xffff0000, v60
	v_lshlrev_b32_e32 v58, 16, v61
	v_and_b32_e32 v59, 0xffff0000, v61
	v_lshlrev_b32_e32 v110, 16, v62
	v_and_b32_e32 v111, 0xffff0000, v62
	v_lshlrev_b32_e32 v112, 16, v63
	v_and_b32_e32 v113, 0xffff0000, v63
	v_pk_fma_f32 v[48:49], v[48:49], v[64:65], v[56:57] op_sel_hi:[1,0,1]
	v_pk_fma_f32 v[44:45], v[44:45], v[64:65], v[58:59] op_sel:[0,1,0]
	v_pk_fma_f32 v[46:47], v[46:47], v[66:67], v[110:111] op_sel_hi:[1,0,1]
	v_pk_fma_f32 v[40:41], v[40:41], v[66:67], v[112:113] op_sel:[0,1,0]
	s_add_u32 s4, s4, 0x40000
	s_addc_u32 s5, s5, 0
	global_load_dword v60, v6, s[0:1]
	global_load_dword v64, v36, s[12:13] offset:384
	global_load_dword v61, v7, s[0:1]
	global_load_dword v65, v34, s[12:13] offset:384
	global_load_dword v62, v8, s[0:1]
	global_load_dword v66, v32, s[12:13] offset:384
	global_load_dword v63, v9, s[0:1]
	global_load_dword v67, v30, s[12:13] offset:384
	s_add_u32 s0, s0, 0x40000
	s_addc_u32 s1, s1, 0
	s_waitcnt vmcnt(44)
	v_cvt_pk_bf16_f32 v52, v48, v49
	v_cvt_pk_bf16_f32 v53, v44, v45
	v_cvt_pk_bf16_f32 v54, v46, v47
	v_cvt_pk_bf16_f32 v55, v40, v41
	global_store_dword v6, v52, s[4:5]
	global_store_dword v7, v53, s[4:5]
	global_store_dword v8, v54, s[4:5]
	global_store_dword v9, v55, s[4:5]
	v_lshlrev_b32_e32 v56, 16, v68
	v_and_b32_e32 v57, 0xffff0000, v68
	v_lshlrev_b32_e32 v58, 16, v69
	v_and_b32_e32 v59, 0xffff0000, v69
	v_lshlrev_b32_e32 v110, 16, v70
	v_and_b32_e32 v111, 0xffff0000, v70
	v_lshlrev_b32_e32 v112, 16, v71
	v_and_b32_e32 v113, 0xffff0000, v71
	v_pk_fma_f32 v[48:49], v[48:49], v[72:73], v[56:57] op_sel_hi:[1,0,1]
	v_pk_fma_f32 v[44:45], v[44:45], v[72:73], v[58:59] op_sel:[0,1,0]
	v_pk_fma_f32 v[46:47], v[46:47], v[74:75], v[110:111] op_sel_hi:[1,0,1]
	v_pk_fma_f32 v[40:41], v[40:41], v[74:75], v[112:113] op_sel:[0,1,0]
	s_add_u32 s4, s4, 0x40000
	s_addc_u32 s5, s5, 0
	global_load_dword v68, v6, s[0:1]
	global_load_dword v72, v36, s[12:13] offset:448
	global_load_dword v69, v7, s[0:1]
	global_load_dword v73, v34, s[12:13] offset:448
	global_load_dword v70, v8, s[0:1]
	global_load_dword v74, v32, s[12:13] offset:448
	global_load_dword v71, v9, s[0:1]
	global_load_dword v75, v30, s[12:13] offset:448
	s_add_u32 s0, s0, 0x40000
	s_addc_u32 s1, s1, 0
	s_waitcnt vmcnt(48)
	v_cvt_pk_bf16_f32 v52, v48, v49
	v_cvt_pk_bf16_f32 v53, v44, v45
	v_cvt_pk_bf16_f32 v54, v46, v47
	v_cvt_pk_bf16_f32 v55, v40, v41
	global_store_dword v6, v52, s[4:5]
	global_store_dword v7, v53, s[4:5]
	global_store_dword v8, v54, s[4:5]
	global_store_dword v9, v55, s[4:5]
	v_lshlrev_b32_e32 v56, 16, v76
	v_and_b32_e32 v57, 0xffff0000, v76
	v_lshlrev_b32_e32 v58, 16, v77
	v_and_b32_e32 v59, 0xffff0000, v77
	v_lshlrev_b32_e32 v110, 16, v78
	v_and_b32_e32 v111, 0xffff0000, v78
	v_lshlrev_b32_e32 v112, 16, v79
	v_and_b32_e32 v113, 0xffff0000, v79
	v_pk_fma_f32 v[48:49], v[48:49], v[80:81], v[56:57] op_sel_hi:[1,0,1]
	v_pk_fma_f32 v[44:45], v[44:45], v[80:81], v[58:59] op_sel:[0,1,0]
	v_pk_fma_f32 v[46:47], v[46:47], v[82:83], v[110:111] op_sel_hi:[1,0,1]
	v_pk_fma_f32 v[40:41], v[40:41], v[82:83], v[112:113] op_sel:[0,1,0]
	s_add_u32 s4, s4, 0x40000
	s_addc_u32 s5, s5, 0
	global_load_dword v76, v6, s[0:1]
	global_load_dword v80, v36, s[12:13] offset:512
	global_load_dword v77, v7, s[0:1]
	global_load_dword v81, v34, s[12:13] offset:512
	global_load_dword v78, v8, s[0:1]
	global_load_dword v82, v32, s[12:13] offset:512
	global_load_dword v79, v9, s[0:1]
	global_load_dword v83, v30, s[12:13] offset:512
	s_add_u32 s0, s0, 0x40000
	s_addc_u32 s1, s1, 0
	s_waitcnt vmcnt(52)
	v_cvt_pk_bf16_f32 v52, v48, v49
	v_cvt_pk_bf16_f32 v53, v44, v45
	v_cvt_pk_bf16_f32 v54, v46, v47
	v_cvt_pk_bf16_f32 v55, v40, v41
	global_store_dword v6, v52, s[4:5]
	global_store_dword v7, v53, s[4:5]
	global_store_dword v8, v54, s[4:5]
	global_store_dword v9, v55, s[4:5]
	v_lshlrev_b32_e32 v56, 16, v84
	v_and_b32_e32 v57, 0xffff0000, v84
	v_lshlrev_b32_e32 v58, 16, v85
	v_and_b32_e32 v59, 0xffff0000, v85
	v_lshlrev_b32_e32 v110, 16, v86
	v_and_b32_e32 v111, 0xffff0000, v86
	v_lshlrev_b32_e32 v112, 16, v87
	v_and_b32_e32 v113, 0xffff0000, v87
	v_pk_fma_f32 v[48:49], v[48:49], v[88:89], v[56:57] op_sel_hi:[1,0,1]
	v_pk_fma_f32 v[44:45], v[44:45], v[88:89], v[58:59] op_sel:[0,1,0]
	v_pk_fma_f32 v[46:47], v[46:47], v[90:91], v[110:111] op_sel_hi:[1,0,1]
	v_pk_fma_f32 v[40:41], v[40:41], v[90:91], v[112:113] op_sel:[0,1,0]
	s_add_u32 s4, s4, 0x40000
	s_addc_u32 s5, s5, 0
	global_load_dword v84, v6, s[0:1]
	global_load_dword v88, v36, s[12:13] offset:576
	global_load_dword v85, v7, s[0:1]
	global_load_dword v89, v34, s[12:13] offset:576
	global_load_dword v86, v8, s[0:1]
	global_load_dword v90, v32, s[12:13] offset:576
	global_load_dword v87, v9, s[0:1]
	global_load_dword v91, v30, s[12:13] offset:576
	s_add_u32 s0, s0, 0x40000
	s_addc_u32 s1, s1, 0
	s_waitcnt vmcnt(56)
	v_cvt_pk_bf16_f32 v52, v48, v49
	v_cvt_pk_bf16_f32 v53, v44, v45
	v_cvt_pk_bf16_f32 v54, v46, v47
	v_cvt_pk_bf16_f32 v55, v40, v41
	global_store_dword v6, v52, s[4:5]
	global_store_dword v7, v53, s[4:5]
	global_store_dword v8, v54, s[4:5]
	global_store_dword v9, v55, s[4:5]
	v_lshlrev_b32_e32 v56, 16, v92
	v_and_b32_e32 v57, 0xffff0000, v92
	v_lshlrev_b32_e32 v58, 16, v93
	v_and_b32_e32 v59, 0xffff0000, v93
	v_lshlrev_b32_e32 v110, 16, v94
	v_and_b32_e32 v111, 0xffff0000, v94
	v_lshlrev_b32_e32 v112, 16, v95
	v_and_b32_e32 v113, 0xffff0000, v95
	v_pk_fma_f32 v[48:49], v[48:49], v[96:97], v[56:57] op_sel_hi:[1,0,1]
	v_pk_fma_f32 v[44:45], v[44:45], v[96:97], v[58:59] op_sel:[0,1,0]
	v_pk_fma_f32 v[46:47], v[46:47], v[98:99], v[110:111] op_sel_hi:[1,0,1]
	v_pk_fma_f32 v[40:41], v[40:41], v[98:99], v[112:113] op_sel:[0,1,0]
	s_add_u32 s4, s4, 0x40000
	s_addc_u32 s5, s5, 0
	global_load_dword v92, v6, s[0:1]
	global_load_dword v96, v36, s[12:13] offset:640
	global_load_dword v93, v7, s[0:1]
	global_load_dword v97, v34, s[12:13] offset:640
	global_load_dword v94, v8, s[0:1]
	global_load_dword v98, v32, s[12:13] offset:640
	global_load_dword v95, v9, s[0:1]
	global_load_dword v99, v30, s[12:13] offset:640
	s_add_u32 s0, s0, 0x40000
	s_addc_u32 s1, s1, 0
	s_waitcnt vmcnt(60)
	v_cvt_pk_bf16_f32 v52, v48, v49
	v_cvt_pk_bf16_f32 v53, v44, v45
	v_cvt_pk_bf16_f32 v54, v46, v47
	v_cvt_pk_bf16_f32 v55, v40, v41
	global_store_dword v6, v52, s[4:5]
	global_store_dword v7, v53, s[4:5]
	global_store_dword v8, v54, s[4:5]
	global_store_dword v9, v55, s[4:5]
	v_lshlrev_b32_e32 v56, 16, v100
	v_and_b32_e32 v57, 0xffff0000, v100
	v_lshlrev_b32_e32 v58, 16, v101
	v_and_b32_e32 v59, 0xffff0000, v101
	v_lshlrev_b32_e32 v110, 16, v102
	v_and_b32_e32 v111, 0xffff0000, v102
	v_lshlrev_b32_e32 v112, 16, v103
	v_and_b32_e32 v113, 0xffff0000, v103
	v_pk_fma_f32 v[48:49], v[48:49], v[104:105], v[56:57] op_sel_hi:[1,0,1]
	v_pk_fma_f32 v[44:45], v[44:45], v[104:105], v[58:59] op_sel:[0,1,0]
	v_pk_fma_f32 v[46:47], v[46:47], v[106:107], v[110:111] op_sel_hi:[1,0,1]
	v_pk_fma_f32 v[40:41], v[40:41], v[106:107], v[112:113] op_sel:[0,1,0]
	s_add_u32 s4, s4, 0x40000
	s_addc_u32 s5, s5, 0
	global_load_dword v100, v6, s[0:1]
	global_load_dword v104, v36, s[12:13] offset:704
	global_load_dword v101, v7, s[0:1]
	global_load_dword v105, v34, s[12:13] offset:704
	global_load_dword v102, v8, s[0:1]
	global_load_dword v106, v32, s[12:13] offset:704
	global_load_dword v103, v9, s[0:1]
	global_load_dword v107, v30, s[12:13] offset:704
	s_add_u32 s0, s0, 0x40000
	s_addc_u32 s1, s1, 0
	s_waitcnt vmcnt(60)
	v_cvt_pk_bf16_f32 v52, v48, v49
	v_cvt_pk_bf16_f32 v53, v44, v45
	v_cvt_pk_bf16_f32 v54, v46, v47
	v_cvt_pk_bf16_f32 v55, v40, v41
	global_store_dword v6, v52, s[4:5]
	global_store_dword v7, v53, s[4:5]
	global_store_dword v8, v54, s[4:5]
	global_store_dword v9, v55, s[4:5]
	v_lshlrev_b32_e32 v56, 16, v60
	v_and_b32_e32 v57, 0xffff0000, v60
	v_lshlrev_b32_e32 v58, 16, v61
	v_and_b32_e32 v59, 0xffff0000, v61
	v_lshlrev_b32_e32 v110, 16, v62
	v_and_b32_e32 v111, 0xffff0000, v62
	v_lshlrev_b32_e32 v112, 16, v63
	v_and_b32_e32 v113, 0xffff0000, v63
	v_pk_fma_f32 v[48:49], v[48:49], v[64:65], v[56:57] op_sel_hi:[1,0,1]
	v_pk_fma_f32 v[44:45], v[44:45], v[64:65], v[58:59] op_sel:[0,1,0]
	v_pk_fma_f32 v[46:47], v[46:47], v[66:67], v[110:111] op_sel_hi:[1,0,1]
	v_pk_fma_f32 v[40:41], v[40:41], v[66:67], v[112:113] op_sel:[0,1,0]
	s_add_u32 s4, s4, 0x40000
	s_addc_u32 s5, s5, 0
	global_load_dword v60, v6, s[0:1]
	global_load_dword v64, v36, s[12:13] offset:768
	global_load_dword v61, v7, s[0:1]
	global_load_dword v65, v34, s[12:13] offset:768
	global_load_dword v62, v8, s[0:1]
	global_load_dword v66, v32, s[12:13] offset:768
	global_load_dword v63, v9, s[0:1]
	global_load_dword v67, v30, s[12:13] offset:768
	s_add_u32 s0, s0, 0x40000
	s_addc_u32 s1, s1, 0
	s_waitcnt vmcnt(60)
	v_cvt_pk_bf16_f32 v52, v48, v49
	v_cvt_pk_bf16_f32 v53, v44, v45
	v_cvt_pk_bf16_f32 v54, v46, v47
	v_cvt_pk_bf16_f32 v55, v40, v41
	global_store_dword v6, v52, s[4:5]
	global_store_dword v7, v53, s[4:5]
	global_store_dword v8, v54, s[4:5]
	global_store_dword v9, v55, s[4:5]
	v_lshlrev_b32_e32 v56, 16, v68
	v_and_b32_e32 v57, 0xffff0000, v68
	v_lshlrev_b32_e32 v58, 16, v69
	v_and_b32_e32 v59, 0xffff0000, v69
	v_lshlrev_b32_e32 v110, 16, v70
	v_and_b32_e32 v111, 0xffff0000, v70
	v_lshlrev_b32_e32 v112, 16, v71
	v_and_b32_e32 v113, 0xffff0000, v71
	v_pk_fma_f32 v[48:49], v[48:49], v[72:73], v[56:57] op_sel_hi:[1,0,1]
	v_pk_fma_f32 v[44:45], v[44:45], v[72:73], v[58:59] op_sel:[0,1,0]
	v_pk_fma_f32 v[46:47], v[46:47], v[74:75], v[110:111] op_sel_hi:[1,0,1]
	v_pk_fma_f32 v[40:41], v[40:41], v[74:75], v[112:113] op_sel:[0,1,0]
	s_add_u32 s4, s4, 0x40000
	s_addc_u32 s5, s5, 0
	global_load_dword v68, v6, s[0:1]
	global_load_dword v72, v36, s[12:13] offset:832
	global_load_dword v69, v7, s[0:1]
	global_load_dword v73, v34, s[12:13] offset:832
	global_load_dword v70, v8, s[0:1]
	global_load_dword v74, v32, s[12:13] offset:832
	global_load_dword v71, v9, s[0:1]
	global_load_dword v75, v30, s[12:13] offset:832
	s_add_u32 s0, s0, 0x40000
	s_addc_u32 s1, s1, 0
	s_waitcnt vmcnt(60)
	v_cvt_pk_bf16_f32 v52, v48, v49
	v_cvt_pk_bf16_f32 v53, v44, v45
	v_cvt_pk_bf16_f32 v54, v46, v47
	v_cvt_pk_bf16_f32 v55, v40, v41
	global_store_dword v6, v52, s[4:5]
	global_store_dword v7, v53, s[4:5]
	global_store_dword v8, v54, s[4:5]
	global_store_dword v9, v55, s[4:5]
	v_lshlrev_b32_e32 v56, 16, v76
	v_and_b32_e32 v57, 0xffff0000, v76
	v_lshlrev_b32_e32 v58, 16, v77
	v_and_b32_e32 v59, 0xffff0000, v77
	v_lshlrev_b32_e32 v110, 16, v78
	v_and_b32_e32 v111, 0xffff0000, v78
	v_lshlrev_b32_e32 v112, 16, v79
	v_and_b32_e32 v113, 0xffff0000, v79
	v_pk_fma_f32 v[48:49], v[48:49], v[80:81], v[56:57] op_sel_hi:[1,0,1]
	v_pk_fma_f32 v[44:45], v[44:45], v[80:81], v[58:59] op_sel:[0,1,0]
	v_pk_fma_f32 v[46:47], v[46:47], v[82:83], v[110:111] op_sel_hi:[1,0,1]
	v_pk_fma_f32 v[40:41], v[40:41], v[82:83], v[112:113] op_sel:[0,1,0]
	s_add_u32 s4, s4, 0x40000
	s_addc_u32 s5, s5, 0
	global_load_dword v76, v6, s[0:1]
	global_load_dword v80, v36, s[12:13] offset:896
	global_load_dword v77, v7, s[0:1]
	global_load_dword v81, v34, s[12:13] offset:896
	global_load_dword v78, v8, s[0:1]
	global_load_dword v82, v32, s[12:13] offset:896
	global_load_dword v79, v9, s[0:1]
	global_load_dword v83, v30, s[12:13] offset:896
	s_add_u32 s0, s0, 0x40000
	s_addc_u32 s1, s1, 0
	s_waitcnt vmcnt(60)
	v_cvt_pk_bf16_f32 v52, v48, v49
	v_cvt_pk_bf16_f32 v53, v44, v45
	v_cvt_pk_bf16_f32 v54, v46, v47
	v_cvt_pk_bf16_f32 v55, v40, v41
	global_store_dword v6, v52, s[4:5]
	global_store_dword v7, v53, s[4:5]
	global_store_dword v8, v54, s[4:5]
	global_store_dword v9, v55, s[4:5]
	v_lshlrev_b32_e32 v56, 16, v84
	v_and_b32_e32 v57, 0xffff0000, v84
	v_lshlrev_b32_e32 v58, 16, v85
	v_and_b32_e32 v59, 0xffff0000, v85
	v_lshlrev_b32_e32 v110, 16, v86
	v_and_b32_e32 v111, 0xffff0000, v86
	v_lshlrev_b32_e32 v112, 16, v87
	v_and_b32_e32 v113, 0xffff0000, v87
	v_pk_fma_f32 v[48:49], v[48:49], v[88:89], v[56:57] op_sel_hi:[1,0,1]
	v_pk_fma_f32 v[44:45], v[44:45], v[88:89], v[58:59] op_sel:[0,1,0]
	v_pk_fma_f32 v[46:47], v[46:47], v[90:91], v[110:111] op_sel_hi:[1,0,1]
	v_pk_fma_f32 v[40:41], v[40:41], v[90:91], v[112:113] op_sel:[0,1,0]
	s_add_u32 s4, s4, 0x40000
	s_addc_u32 s5, s5, 0
	global_load_dword v84, v6, s[0:1]
	global_load_dword v88, v36, s[12:13] offset:960
	global_load_dword v85, v7, s[0:1]
	global_load_dword v89, v34, s[12:13] offset:960
	global_load_dword v86, v8, s[0:1]
	global_load_dword v90, v32, s[12:13] offset:960
	global_load_dword v87, v9, s[0:1]
	global_load_dword v91, v30, s[12:13] offset:960
	s_add_u32 s0, s0, 0x40000
	s_addc_u32 s1, s1, 0
	s_waitcnt vmcnt(60)
	v_cvt_pk_bf16_f32 v52, v48, v49
	v_cvt_pk_bf16_f32 v53, v44, v45
	v_cvt_pk_bf16_f32 v54, v46, v47
	v_cvt_pk_bf16_f32 v55, v40, v41
	global_store_dword v6, v52, s[4:5]
	global_store_dword v7, v53, s[4:5]
	global_store_dword v8, v54, s[4:5]
	global_store_dword v9, v55, s[4:5]
	v_lshlrev_b32_e32 v56, 16, v92
	v_and_b32_e32 v57, 0xffff0000, v92
	v_lshlrev_b32_e32 v58, 16, v93
	v_and_b32_e32 v59, 0xffff0000, v93
	v_lshlrev_b32_e32 v110, 16, v94
	v_and_b32_e32 v111, 0xffff0000, v94
	v_lshlrev_b32_e32 v112, 16, v95
	v_and_b32_e32 v113, 0xffff0000, v95
	v_pk_fma_f32 v[48:49], v[48:49], v[96:97], v[56:57] op_sel_hi:[1,0,1]
	v_pk_fma_f32 v[44:45], v[44:45], v[96:97], v[58:59] op_sel:[0,1,0]
	v_pk_fma_f32 v[46:47], v[46:47], v[98:99], v[110:111] op_sel_hi:[1,0,1]
	v_pk_fma_f32 v[40:41], v[40:41], v[98:99], v[112:113] op_sel:[0,1,0]
	s_add_u32 s4, s4, 0x40000
	s_addc_u32 s5, s5, 0
	global_load_dword v92, v6, s[0:1]
	global_load_dword v96, v36, s[12:13] offset:1024
	global_load_dword v93, v7, s[0:1]
	global_load_dword v97, v34, s[12:13] offset:1024
	global_load_dword v94, v8, s[0:1]
	global_load_dword v98, v32, s[12:13] offset:1024
	global_load_dword v95, v9, s[0:1]
	global_load_dword v99, v30, s[12:13] offset:1024
	s_add_u32 s0, s0, 0x40000
	s_addc_u32 s1, s1, 0
	s_waitcnt vmcnt(60)
	v_cvt_pk_bf16_f32 v52, v48, v49
	v_cvt_pk_bf16_f32 v53, v44, v45
	v_cvt_pk_bf16_f32 v54, v46, v47
	v_cvt_pk_bf16_f32 v55, v40, v41
	global_store_dword v6, v52, s[4:5]
	global_store_dword v7, v53, s[4:5]
	global_store_dword v8, v54, s[4:5]
	global_store_dword v9, v55, s[4:5]
	v_lshlrev_b32_e32 v56, 16, v100
	v_and_b32_e32 v57, 0xffff0000, v100
	v_lshlrev_b32_e32 v58, 16, v101
	v_and_b32_e32 v59, 0xffff0000, v101
	v_lshlrev_b32_e32 v110, 16, v102
	v_and_b32_e32 v111, 0xffff0000, v102
	v_lshlrev_b32_e32 v112, 16, v103
	v_and_b32_e32 v113, 0xffff0000, v103
	v_pk_fma_f32 v[48:49], v[48:49], v[104:105], v[56:57] op_sel_hi:[1,0,1]
	v_pk_fma_f32 v[44:45], v[44:45], v[104:105], v[58:59] op_sel:[0,1,0]
	v_pk_fma_f32 v[46:47], v[46:47], v[106:107], v[110:111] op_sel_hi:[1,0,1]
	v_pk_fma_f32 v[40:41], v[40:41], v[106:107], v[112:113] op_sel:[0,1,0]
	s_add_u32 s4, s4, 0x40000
	s_addc_u32 s5, s5, 0
	global_load_dword v100, v6, s[0:1]
	global_load_dword v104, v36, s[12:13] offset:1088
	global_load_dword v101, v7, s[0:1]
	global_load_dword v105, v34, s[12:13] offset:1088
	global_load_dword v102, v8, s[0:1]
	global_load_dword v106, v32, s[12:13] offset:1088
	global_load_dword v103, v9, s[0:1]
	global_load_dword v107, v30, s[12:13] offset:1088
	s_add_u32 s0, s0, 0x40000
	s_addc_u32 s1, s1, 0
	s_waitcnt vmcnt(60)
	v_cvt_pk_bf16_f32 v52, v48, v49
	v_cvt_pk_bf16_f32 v53, v44, v45
	v_cvt_pk_bf16_f32 v54, v46, v47
	v_cvt_pk_bf16_f32 v55, v40, v41
	global_store_dword v6, v52, s[4:5]
	global_store_dword v7, v53, s[4:5]
	global_store_dword v8, v54, s[4:5]
	global_store_dword v9, v55, s[4:5]
	v_lshlrev_b32_e32 v56, 16, v60
	v_and_b32_e32 v57, 0xffff0000, v60
	v_lshlrev_b32_e32 v58, 16, v61
	v_and_b32_e32 v59, 0xffff0000, v61
	v_lshlrev_b32_e32 v110, 16, v62
	v_and_b32_e32 v111, 0xffff0000, v62
	v_lshlrev_b32_e32 v112, 16, v63
	v_and_b32_e32 v113, 0xffff0000, v63
	v_pk_fma_f32 v[48:49], v[48:49], v[64:65], v[56:57] op_sel_hi:[1,0,1]
	v_pk_fma_f32 v[44:45], v[44:45], v[64:65], v[58:59] op_sel:[0,1,0]
	v_pk_fma_f32 v[46:47], v[46:47], v[66:67], v[110:111] op_sel_hi:[1,0,1]
	v_pk_fma_f32 v[40:41], v[40:41], v[66:67], v[112:113] op_sel:[0,1,0]
	s_add_u32 s4, s4, 0x40000
	s_addc_u32 s5, s5, 0
	global_load_dword v60, v6, s[0:1]
	global_load_dword v64, v36, s[12:13] offset:1152
	global_load_dword v61, v7, s[0:1]
	global_load_dword v65, v34, s[12:13] offset:1152
	global_load_dword v62, v8, s[0:1]
	global_load_dword v66, v32, s[12:13] offset:1152
	global_load_dword v63, v9, s[0:1]
	global_load_dword v67, v30, s[12:13] offset:1152
	s_add_u32 s0, s0, 0x40000
	s_addc_u32 s1, s1, 0
	s_waitcnt vmcnt(60)
	v_cvt_pk_bf16_f32 v52, v48, v49
	v_cvt_pk_bf16_f32 v53, v44, v45
	v_cvt_pk_bf16_f32 v54, v46, v47
	v_cvt_pk_bf16_f32 v55, v40, v41
	global_store_dword v6, v52, s[4:5]
	global_store_dword v7, v53, s[4:5]
	global_store_dword v8, v54, s[4:5]
	global_store_dword v9, v55, s[4:5]
	v_lshlrev_b32_e32 v56, 16, v68
	v_and_b32_e32 v57, 0xffff0000, v68
	v_lshlrev_b32_e32 v58, 16, v69
	v_and_b32_e32 v59, 0xffff0000, v69
	v_lshlrev_b32_e32 v110, 16, v70
	v_and_b32_e32 v111, 0xffff0000, v70
	v_lshlrev_b32_e32 v112, 16, v71
	v_and_b32_e32 v113, 0xffff0000, v71
	v_pk_fma_f32 v[48:49], v[48:49], v[72:73], v[56:57] op_sel_hi:[1,0,1]
	v_pk_fma_f32 v[44:45], v[44:45], v[72:73], v[58:59] op_sel:[0,1,0]
	v_pk_fma_f32 v[46:47], v[46:47], v[74:75], v[110:111] op_sel_hi:[1,0,1]
	v_pk_fma_f32 v[40:41], v[40:41], v[74:75], v[112:113] op_sel:[0,1,0]
	s_add_u32 s4, s4, 0x40000
	s_addc_u32 s5, s5, 0
	global_load_dword v68, v6, s[0:1]
	global_load_dword v72, v36, s[12:13] offset:1216
	global_load_dword v69, v7, s[0:1]
	global_load_dword v73, v34, s[12:13] offset:1216
	global_load_dword v70, v8, s[0:1]
	global_load_dword v74, v32, s[12:13] offset:1216
	global_load_dword v71, v9, s[0:1]
	global_load_dword v75, v30, s[12:13] offset:1216
	s_add_u32 s0, s0, 0x40000
	s_addc_u32 s1, s1, 0
	s_waitcnt vmcnt(60)
	v_cvt_pk_bf16_f32 v52, v48, v49
	v_cvt_pk_bf16_f32 v53, v44, v45
	v_cvt_pk_bf16_f32 v54, v46, v47
	v_cvt_pk_bf16_f32 v55, v40, v41
	global_store_dword v6, v52, s[4:5]
	global_store_dword v7, v53, s[4:5]
	global_store_dword v8, v54, s[4:5]
	global_store_dword v9, v55, s[4:5]
	v_lshlrev_b32_e32 v56, 16, v76
	v_and_b32_e32 v57, 0xffff0000, v76
	v_lshlrev_b32_e32 v58, 16, v77
	v_and_b32_e32 v59, 0xffff0000, v77
	v_lshlrev_b32_e32 v110, 16, v78
	v_and_b32_e32 v111, 0xffff0000, v78
	v_lshlrev_b32_e32 v112, 16, v79
	v_and_b32_e32 v113, 0xffff0000, v79
	v_pk_fma_f32 v[48:49], v[48:49], v[80:81], v[56:57] op_sel_hi:[1,0,1]
	v_pk_fma_f32 v[44:45], v[44:45], v[80:81], v[58:59] op_sel:[0,1,0]
	v_pk_fma_f32 v[46:47], v[46:47], v[82:83], v[110:111] op_sel_hi:[1,0,1]
	v_pk_fma_f32 v[40:41], v[40:41], v[82:83], v[112:113] op_sel:[0,1,0]
	s_add_u32 s4, s4, 0x40000
	s_addc_u32 s5, s5, 0
	global_load_dword v76, v6, s[0:1]
	global_load_dword v80, v36, s[12:13] offset:1280
	global_load_dword v77, v7, s[0:1]
	global_load_dword v81, v34, s[12:13] offset:1280
	global_load_dword v78, v8, s[0:1]
	global_load_dword v82, v32, s[12:13] offset:1280
	global_load_dword v79, v9, s[0:1]
	global_load_dword v83, v30, s[12:13] offset:1280
	s_add_u32 s0, s0, 0x40000
	s_addc_u32 s1, s1, 0
	s_waitcnt vmcnt(60)
	v_cvt_pk_bf16_f32 v52, v48, v49
	v_cvt_pk_bf16_f32 v53, v44, v45
	v_cvt_pk_bf16_f32 v54, v46, v47
	v_cvt_pk_bf16_f32 v55, v40, v41
	global_store_dword v6, v52, s[4:5]
	global_store_dword v7, v53, s[4:5]
	global_store_dword v8, v54, s[4:5]
	global_store_dword v9, v55, s[4:5]
	v_lshlrev_b32_e32 v56, 16, v84
	v_and_b32_e32 v57, 0xffff0000, v84
	v_lshlrev_b32_e32 v58, 16, v85
	v_and_b32_e32 v59, 0xffff0000, v85
	v_lshlrev_b32_e32 v110, 16, v86
	v_and_b32_e32 v111, 0xffff0000, v86
	v_lshlrev_b32_e32 v112, 16, v87
	v_and_b32_e32 v113, 0xffff0000, v87
	v_pk_fma_f32 v[48:49], v[48:49], v[88:89], v[56:57] op_sel_hi:[1,0,1]
	v_pk_fma_f32 v[44:45], v[44:45], v[88:89], v[58:59] op_sel:[0,1,0]
	v_pk_fma_f32 v[46:47], v[46:47], v[90:91], v[110:111] op_sel_hi:[1,0,1]
	v_pk_fma_f32 v[40:41], v[40:41], v[90:91], v[112:113] op_sel:[0,1,0]
	s_add_u32 s4, s4, 0x40000
	s_addc_u32 s5, s5, 0
	global_load_dword v84, v6, s[0:1]
	global_load_dword v88, v36, s[12:13] offset:1344
	global_load_dword v85, v7, s[0:1]
	global_load_dword v89, v34, s[12:13] offset:1344
	global_load_dword v86, v8, s[0:1]
	global_load_dword v90, v32, s[12:13] offset:1344
	global_load_dword v87, v9, s[0:1]
	global_load_dword v91, v30, s[12:13] offset:1344
	s_add_u32 s0, s0, 0x40000
	s_addc_u32 s1, s1, 0
	s_waitcnt vmcnt(60)
	v_cvt_pk_bf16_f32 v52, v48, v49
	v_cvt_pk_bf16_f32 v53, v44, v45
	v_cvt_pk_bf16_f32 v54, v46, v47
	v_cvt_pk_bf16_f32 v55, v40, v41
	global_store_dword v6, v52, s[4:5]
	global_store_dword v7, v53, s[4:5]
	global_store_dword v8, v54, s[4:5]
	global_store_dword v9, v55, s[4:5]
	v_lshlrev_b32_e32 v56, 16, v92
	v_and_b32_e32 v57, 0xffff0000, v92
	v_lshlrev_b32_e32 v58, 16, v93
	v_and_b32_e32 v59, 0xffff0000, v93
	v_lshlrev_b32_e32 v110, 16, v94
	v_and_b32_e32 v111, 0xffff0000, v94
	v_lshlrev_b32_e32 v112, 16, v95
	v_and_b32_e32 v113, 0xffff0000, v95
	v_pk_fma_f32 v[48:49], v[48:49], v[96:97], v[56:57] op_sel_hi:[1,0,1]
	v_pk_fma_f32 v[44:45], v[44:45], v[96:97], v[58:59] op_sel:[0,1,0]
	v_pk_fma_f32 v[46:47], v[46:47], v[98:99], v[110:111] op_sel_hi:[1,0,1]
	v_pk_fma_f32 v[40:41], v[40:41], v[98:99], v[112:113] op_sel:[0,1,0]
	s_add_u32 s4, s4, 0x40000
	s_addc_u32 s5, s5, 0
	global_load_dword v92, v6, s[0:1]
	global_load_dword v96, v36, s[12:13] offset:1408
	global_load_dword v93, v7, s[0:1]
	global_load_dword v97, v34, s[12:13] offset:1408
	global_load_dword v94, v8, s[0:1]
	global_load_dword v98, v32, s[12:13] offset:1408
	global_load_dword v95, v9, s[0:1]
	global_load_dword v99, v30, s[12:13] offset:1408
	s_add_u32 s0, s0, 0x40000
	s_addc_u32 s1, s1, 0
	s_waitcnt vmcnt(60)
	v_cvt_pk_bf16_f32 v52, v48, v49
	v_cvt_pk_bf16_f32 v53, v44, v45
	v_cvt_pk_bf16_f32 v54, v46, v47
	v_cvt_pk_bf16_f32 v55, v40, v41
	global_store_dword v6, v52, s[4:5]
	global_store_dword v7, v53, s[4:5]
	global_store_dword v8, v54, s[4:5]
	global_store_dword v9, v55, s[4:5]
	v_lshlrev_b32_e32 v56, 16, v100
	v_and_b32_e32 v57, 0xffff0000, v100
	v_lshlrev_b32_e32 v58, 16, v101
	v_and_b32_e32 v59, 0xffff0000, v101
	v_lshlrev_b32_e32 v110, 16, v102
	v_and_b32_e32 v111, 0xffff0000, v102
	v_lshlrev_b32_e32 v112, 16, v103
	v_and_b32_e32 v113, 0xffff0000, v103
	v_pk_fma_f32 v[48:49], v[48:49], v[104:105], v[56:57] op_sel_hi:[1,0,1]
	v_pk_fma_f32 v[44:45], v[44:45], v[104:105], v[58:59] op_sel:[0,1,0]
	v_pk_fma_f32 v[46:47], v[46:47], v[106:107], v[110:111] op_sel_hi:[1,0,1]
	v_pk_fma_f32 v[40:41], v[40:41], v[106:107], v[112:113] op_sel:[0,1,0]
	s_add_u32 s4, s4, 0x40000
	s_addc_u32 s5, s5, 0
	global_load_dword v100, v6, s[0:1]
	global_load_dword v104, v36, s[12:13] offset:1472
	global_load_dword v101, v7, s[0:1]
	global_load_dword v105, v34, s[12:13] offset:1472
	global_load_dword v102, v8, s[0:1]
	global_load_dword v106, v32, s[12:13] offset:1472
	global_load_dword v103, v9, s[0:1]
	global_load_dword v107, v30, s[12:13] offset:1472
	s_add_u32 s0, s0, 0x40000
	s_addc_u32 s1, s1, 0
	s_waitcnt vmcnt(60)
	v_cvt_pk_bf16_f32 v52, v48, v49
	v_cvt_pk_bf16_f32 v53, v44, v45
	v_cvt_pk_bf16_f32 v54, v46, v47
	v_cvt_pk_bf16_f32 v55, v40, v41
	global_store_dword v6, v52, s[4:5]
	global_store_dword v7, v53, s[4:5]
	global_store_dword v8, v54, s[4:5]
	global_store_dword v9, v55, s[4:5]
	v_lshlrev_b32_e32 v56, 16, v60
	v_and_b32_e32 v57, 0xffff0000, v60
	v_lshlrev_b32_e32 v58, 16, v61
	v_and_b32_e32 v59, 0xffff0000, v61
	v_lshlrev_b32_e32 v110, 16, v62
	v_and_b32_e32 v111, 0xffff0000, v62
	v_lshlrev_b32_e32 v112, 16, v63
	v_and_b32_e32 v113, 0xffff0000, v63
	v_pk_fma_f32 v[48:49], v[48:49], v[64:65], v[56:57] op_sel_hi:[1,0,1]
	v_pk_fma_f32 v[44:45], v[44:45], v[64:65], v[58:59] op_sel:[0,1,0]
	v_pk_fma_f32 v[46:47], v[46:47], v[66:67], v[110:111] op_sel_hi:[1,0,1]
	v_pk_fma_f32 v[40:41], v[40:41], v[66:67], v[112:113] op_sel:[0,1,0]
	s_add_u32 s4, s4, 0x40000
	s_addc_u32 s5, s5, 0
	global_load_dword v60, v6, s[0:1]
	global_load_dword v64, v36, s[12:13] offset:1536
	global_load_dword v61, v7, s[0:1]
	global_load_dword v65, v34, s[12:13] offset:1536
	global_load_dword v62, v8, s[0:1]
	global_load_dword v66, v32, s[12:13] offset:1536
	global_load_dword v63, v9, s[0:1]
	global_load_dword v67, v30, s[12:13] offset:1536
	s_add_u32 s0, s0, 0x40000
	s_addc_u32 s1, s1, 0
	s_waitcnt vmcnt(60)
	v_cvt_pk_bf16_f32 v52, v48, v49
	v_cvt_pk_bf16_f32 v53, v44, v45
	v_cvt_pk_bf16_f32 v54, v46, v47
	v_cvt_pk_bf16_f32 v55, v40, v41
	global_store_dword v6, v52, s[4:5]
	global_store_dword v7, v53, s[4:5]
	global_store_dword v8, v54, s[4:5]
	global_store_dword v9, v55, s[4:5]
	v_lshlrev_b32_e32 v56, 16, v68
	v_and_b32_e32 v57, 0xffff0000, v68
	v_lshlrev_b32_e32 v58, 16, v69
	v_and_b32_e32 v59, 0xffff0000, v69
	v_lshlrev_b32_e32 v110, 16, v70
	v_and_b32_e32 v111, 0xffff0000, v70
	v_lshlrev_b32_e32 v112, 16, v71
	v_and_b32_e32 v113, 0xffff0000, v71
	v_pk_fma_f32 v[48:49], v[48:49], v[72:73], v[56:57] op_sel_hi:[1,0,1]
	v_pk_fma_f32 v[44:45], v[44:45], v[72:73], v[58:59] op_sel:[0,1,0]
	v_pk_fma_f32 v[46:47], v[46:47], v[74:75], v[110:111] op_sel_hi:[1,0,1]
	v_pk_fma_f32 v[40:41], v[40:41], v[74:75], v[112:113] op_sel:[0,1,0]
	s_add_u32 s4, s4, 0x40000
	s_addc_u32 s5, s5, 0
	global_load_dword v68, v6, s[0:1]
	global_load_dword v72, v36, s[12:13] offset:1600
	global_load_dword v69, v7, s[0:1]
	global_load_dword v73, v34, s[12:13] offset:1600
	global_load_dword v70, v8, s[0:1]
	global_load_dword v74, v32, s[12:13] offset:1600
	global_load_dword v71, v9, s[0:1]
	global_load_dword v75, v30, s[12:13] offset:1600
	s_add_u32 s0, s0, 0x40000
	s_addc_u32 s1, s1, 0
	s_waitcnt vmcnt(60)
	v_cvt_pk_bf16_f32 v52, v48, v49
	v_cvt_pk_bf16_f32 v53, v44, v45
	v_cvt_pk_bf16_f32 v54, v46, v47
	v_cvt_pk_bf16_f32 v55, v40, v41
	global_store_dword v6, v52, s[4:5]
	global_store_dword v7, v53, s[4:5]
	global_store_dword v8, v54, s[4:5]
	global_store_dword v9, v55, s[4:5]
	v_lshlrev_b32_e32 v56, 16, v76
	v_and_b32_e32 v57, 0xffff0000, v76
	v_lshlrev_b32_e32 v58, 16, v77
	v_and_b32_e32 v59, 0xffff0000, v77
	v_lshlrev_b32_e32 v110, 16, v78
	v_and_b32_e32 v111, 0xffff0000, v78
	v_lshlrev_b32_e32 v112, 16, v79
	v_and_b32_e32 v113, 0xffff0000, v79
	v_pk_fma_f32 v[48:49], v[48:49], v[80:81], v[56:57] op_sel_hi:[1,0,1]
	v_pk_fma_f32 v[44:45], v[44:45], v[80:81], v[58:59] op_sel:[0,1,0]
	v_pk_fma_f32 v[46:47], v[46:47], v[82:83], v[110:111] op_sel_hi:[1,0,1]
	v_pk_fma_f32 v[40:41], v[40:41], v[82:83], v[112:113] op_sel:[0,1,0]
	s_add_u32 s4, s4, 0x40000
	s_addc_u32 s5, s5, 0
	global_load_dword v76, v6, s[0:1]
	global_load_dword v80, v36, s[12:13] offset:1664
	global_load_dword v77, v7, s[0:1]
	global_load_dword v81, v34, s[12:13] offset:1664
	global_load_dword v78, v8, s[0:1]
	global_load_dword v82, v32, s[12:13] offset:1664
	global_load_dword v79, v9, s[0:1]
	global_load_dword v83, v30, s[12:13] offset:1664
	s_add_u32 s0, s0, 0x40000
	s_addc_u32 s1, s1, 0
	s_waitcnt vmcnt(60)
	v_cvt_pk_bf16_f32 v52, v48, v49
	v_cvt_pk_bf16_f32 v53, v44, v45
	v_cvt_pk_bf16_f32 v54, v46, v47
	v_cvt_pk_bf16_f32 v55, v40, v41
	global_store_dword v6, v52, s[4:5]
	global_store_dword v7, v53, s[4:5]
	global_store_dword v8, v54, s[4:5]
	global_store_dword v9, v55, s[4:5]
	v_lshlrev_b32_e32 v56, 16, v84
	v_and_b32_e32 v57, 0xffff0000, v84
	v_lshlrev_b32_e32 v58, 16, v85
	v_and_b32_e32 v59, 0xffff0000, v85
	v_lshlrev_b32_e32 v110, 16, v86
	v_and_b32_e32 v111, 0xffff0000, v86
	v_lshlrev_b32_e32 v112, 16, v87
	v_and_b32_e32 v113, 0xffff0000, v87
	v_pk_fma_f32 v[48:49], v[48:49], v[88:89], v[56:57] op_sel_hi:[1,0,1]
	v_pk_fma_f32 v[44:45], v[44:45], v[88:89], v[58:59] op_sel:[0,1,0]
	v_pk_fma_f32 v[46:47], v[46:47], v[90:91], v[110:111] op_sel_hi:[1,0,1]
	v_pk_fma_f32 v[40:41], v[40:41], v[90:91], v[112:113] op_sel:[0,1,0]
	s_add_u32 s4, s4, 0x40000
	s_addc_u32 s5, s5, 0
	global_load_dword v84, v6, s[0:1]
	global_load_dword v88, v36, s[12:13] offset:1728
	global_load_dword v85, v7, s[0:1]
	global_load_dword v89, v34, s[12:13] offset:1728
	global_load_dword v86, v8, s[0:1]
	global_load_dword v90, v32, s[12:13] offset:1728
	global_load_dword v87, v9, s[0:1]
	global_load_dword v91, v30, s[12:13] offset:1728
	s_add_u32 s0, s0, 0x40000
	s_addc_u32 s1, s1, 0
	s_waitcnt vmcnt(60)
	v_cvt_pk_bf16_f32 v52, v48, v49
	v_cvt_pk_bf16_f32 v53, v44, v45
	v_cvt_pk_bf16_f32 v54, v46, v47
	v_cvt_pk_bf16_f32 v55, v40, v41
	global_store_dword v6, v52, s[4:5]
	global_store_dword v7, v53, s[4:5]
	global_store_dword v8, v54, s[4:5]
	global_store_dword v9, v55, s[4:5]
	v_lshlrev_b32_e32 v56, 16, v92
	v_and_b32_e32 v57, 0xffff0000, v92
	v_lshlrev_b32_e32 v58, 16, v93
	v_and_b32_e32 v59, 0xffff0000, v93
	v_lshlrev_b32_e32 v110, 16, v94
	v_and_b32_e32 v111, 0xffff0000, v94
	v_lshlrev_b32_e32 v112, 16, v95
	v_and_b32_e32 v113, 0xffff0000, v95
	v_pk_fma_f32 v[48:49], v[48:49], v[96:97], v[56:57] op_sel_hi:[1,0,1]
	v_pk_fma_f32 v[44:45], v[44:45], v[96:97], v[58:59] op_sel:[0,1,0]
	v_pk_fma_f32 v[46:47], v[46:47], v[98:99], v[110:111] op_sel_hi:[1,0,1]
	v_pk_fma_f32 v[40:41], v[40:41], v[98:99], v[112:113] op_sel:[0,1,0]
	s_add_u32 s4, s4, 0x40000
	s_addc_u32 s5, s5, 0
	global_load_dword v92, v6, s[0:1]
	global_load_dword v96, v36, s[12:13] offset:1792
	global_load_dword v93, v7, s[0:1]
	global_load_dword v97, v34, s[12:13] offset:1792
	global_load_dword v94, v8, s[0:1]
	global_load_dword v98, v32, s[12:13] offset:1792
	global_load_dword v95, v9, s[0:1]
	global_load_dword v99, v30, s[12:13] offset:1792
	s_add_u32 s0, s0, 0x40000
	s_addc_u32 s1, s1, 0
	s_waitcnt vmcnt(60)
	v_cvt_pk_bf16_f32 v52, v48, v49
	v_cvt_pk_bf16_f32 v53, v44, v45
	v_cvt_pk_bf16_f32 v54, v46, v47
	v_cvt_pk_bf16_f32 v55, v40, v41
	global_store_dword v6, v52, s[4:5]
	global_store_dword v7, v53, s[4:5]
	global_store_dword v8, v54, s[4:5]
	global_store_dword v9, v55, s[4:5]
	v_lshlrev_b32_e32 v56, 16, v100
	v_and_b32_e32 v57, 0xffff0000, v100
	v_lshlrev_b32_e32 v58, 16, v101
	v_and_b32_e32 v59, 0xffff0000, v101
	v_lshlrev_b32_e32 v110, 16, v102
	v_and_b32_e32 v111, 0xffff0000, v102
	v_lshlrev_b32_e32 v112, 16, v103
	v_and_b32_e32 v113, 0xffff0000, v103
	v_pk_fma_f32 v[48:49], v[48:49], v[104:105], v[56:57] op_sel_hi:[1,0,1]
	v_pk_fma_f32 v[44:45], v[44:45], v[104:105], v[58:59] op_sel:[0,1,0]
	v_pk_fma_f32 v[46:47], v[46:47], v[106:107], v[110:111] op_sel_hi:[1,0,1]
	v_pk_fma_f32 v[40:41], v[40:41], v[106:107], v[112:113] op_sel:[0,1,0]
	s_add_u32 s4, s4, 0x40000
	s_addc_u32 s5, s5, 0
	global_load_dword v100, v6, s[0:1]
	global_load_dword v104, v36, s[12:13] offset:1856
	global_load_dword v101, v7, s[0:1]
	global_load_dword v105, v34, s[12:13] offset:1856
	global_load_dword v102, v8, s[0:1]
	global_load_dword v106, v32, s[12:13] offset:1856
	global_load_dword v103, v9, s[0:1]
	global_load_dword v107, v30, s[12:13] offset:1856
	s_add_u32 s0, s0, 0x40000
	s_addc_u32 s1, s1, 0
	s_waitcnt vmcnt(60)
	v_cvt_pk_bf16_f32 v52, v48, v49
	v_cvt_pk_bf16_f32 v53, v44, v45
	v_cvt_pk_bf16_f32 v54, v46, v47
	v_cvt_pk_bf16_f32 v55, v40, v41
	global_store_dword v6, v52, s[4:5]
	global_store_dword v7, v53, s[4:5]
	global_store_dword v8, v54, s[4:5]
	global_store_dword v9, v55, s[4:5]
	v_lshlrev_b32_e32 v56, 16, v60
	v_and_b32_e32 v57, 0xffff0000, v60
	v_lshlrev_b32_e32 v58, 16, v61
	v_and_b32_e32 v59, 0xffff0000, v61
	v_lshlrev_b32_e32 v110, 16, v62
	v_and_b32_e32 v111, 0xffff0000, v62
	v_lshlrev_b32_e32 v112, 16, v63
	v_and_b32_e32 v113, 0xffff0000, v63
	v_pk_fma_f32 v[48:49], v[48:49], v[64:65], v[56:57] op_sel_hi:[1,0,1]
	v_pk_fma_f32 v[44:45], v[44:45], v[64:65], v[58:59] op_sel:[0,1,0]
	v_pk_fma_f32 v[46:47], v[46:47], v[66:67], v[110:111] op_sel_hi:[1,0,1]
	v_pk_fma_f32 v[40:41], v[40:41], v[66:67], v[112:113] op_sel:[0,1,0]
	s_add_u32 s4, s4, 0x40000
	s_addc_u32 s5, s5, 0
	global_load_dword v60, v6, s[0:1]
	global_load_dword v64, v36, s[12:13] offset:1920
	global_load_dword v61, v7, s[0:1]
	global_load_dword v65, v34, s[12:13] offset:1920
	global_load_dword v62, v8, s[0:1]
	global_load_dword v66, v32, s[12:13] offset:1920
	global_load_dword v63, v9, s[0:1]
	global_load_dword v67, v30, s[12:13] offset:1920
	s_add_u32 s0, s0, 0x40000
	s_addc_u32 s1, s1, 0
	s_waitcnt vmcnt(60)
	v_cvt_pk_bf16_f32 v52, v48, v49
	v_cvt_pk_bf16_f32 v53, v44, v45
	v_cvt_pk_bf16_f32 v54, v46, v47
	v_cvt_pk_bf16_f32 v55, v40, v41
	global_store_dword v6, v52, s[4:5]
	global_store_dword v7, v53, s[4:5]
	global_store_dword v8, v54, s[4:5]
	global_store_dword v9, v55, s[4:5]
	v_lshlrev_b32_e32 v56, 16, v68
	v_and_b32_e32 v57, 0xffff0000, v68
	v_lshlrev_b32_e32 v58, 16, v69
	v_and_b32_e32 v59, 0xffff0000, v69
	v_lshlrev_b32_e32 v110, 16, v70
	v_and_b32_e32 v111, 0xffff0000, v70
	v_lshlrev_b32_e32 v112, 16, v71
	v_and_b32_e32 v113, 0xffff0000, v71
	v_pk_fma_f32 v[48:49], v[48:49], v[72:73], v[56:57] op_sel_hi:[1,0,1]
	v_pk_fma_f32 v[44:45], v[44:45], v[72:73], v[58:59] op_sel:[0,1,0]
	v_pk_fma_f32 v[46:47], v[46:47], v[74:75], v[110:111] op_sel_hi:[1,0,1]
	v_pk_fma_f32 v[40:41], v[40:41], v[74:75], v[112:113] op_sel:[0,1,0]
	s_add_u32 s4, s4, 0x40000
	s_addc_u32 s5, s5, 0
	global_load_dword v68, v6, s[0:1]
	global_load_dword v72, v36, s[12:13] offset:1984
	global_load_dword v69, v7, s[0:1]
	global_load_dword v73, v34, s[12:13] offset:1984
	global_load_dword v70, v8, s[0:1]
	global_load_dword v74, v32, s[12:13] offset:1984
	global_load_dword v71, v9, s[0:1]
	global_load_dword v75, v30, s[12:13] offset:1984
	s_add_u32 s0, s0, 0x40000
	s_addc_u32 s1, s1, 0
	s_waitcnt vmcnt(60)
	v_cvt_pk_bf16_f32 v52, v48, v49
	v_cvt_pk_bf16_f32 v53, v44, v45
	v_cvt_pk_bf16_f32 v54, v46, v47
	v_cvt_pk_bf16_f32 v55, v40, v41
	global_store_dword v6, v52, s[4:5]
	global_store_dword v7, v53, s[4:5]
	global_store_dword v8, v54, s[4:5]
	global_store_dword v9, v55, s[4:5]
	v_lshlrev_b32_e32 v56, 16, v76
	v_and_b32_e32 v57, 0xffff0000, v76
	v_lshlrev_b32_e32 v58, 16, v77
	v_and_b32_e32 v59, 0xffff0000, v77
	v_lshlrev_b32_e32 v110, 16, v78
	v_and_b32_e32 v111, 0xffff0000, v78
	v_lshlrev_b32_e32 v112, 16, v79
	v_and_b32_e32 v113, 0xffff0000, v79
	v_pk_fma_f32 v[48:49], v[48:49], v[80:81], v[56:57] op_sel_hi:[1,0,1]
	v_pk_fma_f32 v[44:45], v[44:45], v[80:81], v[58:59] op_sel:[0,1,0]
	v_pk_fma_f32 v[46:47], v[46:47], v[82:83], v[110:111] op_sel_hi:[1,0,1]
	v_pk_fma_f32 v[40:41], v[40:41], v[82:83], v[112:113] op_sel:[0,1,0]
	s_add_u32 s4, s4, 0x40000
	s_addc_u32 s5, s5, 0
	s_waitcnt vmcnt(52)
	v_cvt_pk_bf16_f32 v52, v48, v49
	v_cvt_pk_bf16_f32 v53, v44, v45
	v_cvt_pk_bf16_f32 v54, v46, v47
	v_cvt_pk_bf16_f32 v55, v40, v41
	global_store_dword v6, v52, s[4:5]
	global_store_dword v7, v53, s[4:5]
	global_store_dword v8, v54, s[4:5]
	global_store_dword v9, v55, s[4:5]
	v_lshlrev_b32_e32 v56, 16, v84
	v_and_b32_e32 v57, 0xffff0000, v84
	v_lshlrev_b32_e32 v58, 16, v85
	v_and_b32_e32 v59, 0xffff0000, v85
	v_lshlrev_b32_e32 v110, 16, v86
	v_and_b32_e32 v111, 0xffff0000, v86
	v_lshlrev_b32_e32 v112, 16, v87
	v_and_b32_e32 v113, 0xffff0000, v87
	v_pk_fma_f32 v[48:49], v[48:49], v[88:89], v[56:57] op_sel_hi:[1,0,1]
	v_pk_fma_f32 v[44:45], v[44:45], v[88:89], v[58:59] op_sel:[0,1,0]
	v_pk_fma_f32 v[46:47], v[46:47], v[90:91], v[110:111] op_sel_hi:[1,0,1]
	v_pk_fma_f32 v[40:41], v[40:41], v[90:91], v[112:113] op_sel:[0,1,0]
	s_add_u32 s4, s4, 0x40000
	s_addc_u32 s5, s5, 0
	s_waitcnt vmcnt(44)
	v_cvt_pk_bf16_f32 v52, v48, v49
	v_cvt_pk_bf16_f32 v53, v44, v45
	v_cvt_pk_bf16_f32 v54, v46, v47
	v_cvt_pk_bf16_f32 v55, v40, v41
	global_store_dword v6, v52, s[4:5]
	global_store_dword v7, v53, s[4:5]
	global_store_dword v8, v54, s[4:5]
	global_store_dword v9, v55, s[4:5]
	v_lshlrev_b32_e32 v56, 16, v92
	v_and_b32_e32 v57, 0xffff0000, v92
	v_lshlrev_b32_e32 v58, 16, v93
	v_and_b32_e32 v59, 0xffff0000, v93
	v_lshlrev_b32_e32 v110, 16, v94
	v_and_b32_e32 v111, 0xffff0000, v94
	v_lshlrev_b32_e32 v112, 16, v95
	v_and_b32_e32 v113, 0xffff0000, v95
	v_pk_fma_f32 v[48:49], v[48:49], v[96:97], v[56:57] op_sel_hi:[1,0,1]
	v_pk_fma_f32 v[44:45], v[44:45], v[96:97], v[58:59] op_sel:[0,1,0]
	v_pk_fma_f32 v[46:47], v[46:47], v[98:99], v[110:111] op_sel_hi:[1,0,1]
	v_pk_fma_f32 v[40:41], v[40:41], v[98:99], v[112:113] op_sel:[0,1,0]
	s_add_u32 s4, s4, 0x40000
	s_addc_u32 s5, s5, 0
	s_waitcnt vmcnt(36)
	v_cvt_pk_bf16_f32 v52, v48, v49
	v_cvt_pk_bf16_f32 v53, v44, v45
	v_cvt_pk_bf16_f32 v54, v46, v47
	v_cvt_pk_bf16_f32 v55, v40, v41
	global_store_dword v6, v52, s[4:5]
	global_store_dword v7, v53, s[4:5]
	global_store_dword v8, v54, s[4:5]
	global_store_dword v9, v55, s[4:5]
	v_lshlrev_b32_e32 v56, 16, v100
	v_and_b32_e32 v57, 0xffff0000, v100
	v_lshlrev_b32_e32 v58, 16, v101
	v_and_b32_e32 v59, 0xffff0000, v101
	v_lshlrev_b32_e32 v110, 16, v102
	v_and_b32_e32 v111, 0xffff0000, v102
	v_lshlrev_b32_e32 v112, 16, v103
	v_and_b32_e32 v113, 0xffff0000, v103
	v_pk_fma_f32 v[48:49], v[48:49], v[104:105], v[56:57] op_sel_hi:[1,0,1]
	v_pk_fma_f32 v[44:45], v[44:45], v[104:105], v[58:59] op_sel:[0,1,0]
	v_pk_fma_f32 v[46:47], v[46:47], v[106:107], v[110:111] op_sel_hi:[1,0,1]
	v_pk_fma_f32 v[40:41], v[40:41], v[106:107], v[112:113] op_sel:[0,1,0]
	s_add_u32 s4, s4, 0x40000
	s_addc_u32 s5, s5, 0
	s_waitcnt vmcnt(28)
	v_cvt_pk_bf16_f32 v52, v48, v49
	v_cvt_pk_bf16_f32 v53, v44, v45
	v_cvt_pk_bf16_f32 v54, v46, v47
	v_cvt_pk_bf16_f32 v55, v40, v41
	global_store_dword v6, v52, s[4:5]
	global_store_dword v7, v53, s[4:5]
	global_store_dword v8, v54, s[4:5]
	global_store_dword v9, v55, s[4:5]
	v_lshlrev_b32_e32 v56, 16, v60
	v_and_b32_e32 v57, 0xffff0000, v60
	v_lshlrev_b32_e32 v58, 16, v61
	v_and_b32_e32 v59, 0xffff0000, v61
	v_lshlrev_b32_e32 v110, 16, v62
	v_and_b32_e32 v111, 0xffff0000, v62
	v_lshlrev_b32_e32 v112, 16, v63
	v_and_b32_e32 v113, 0xffff0000, v63
	v_pk_fma_f32 v[48:49], v[48:49], v[64:65], v[56:57] op_sel_hi:[1,0,1]
	v_pk_fma_f32 v[44:45], v[44:45], v[64:65], v[58:59] op_sel:[0,1,0]
	v_pk_fma_f32 v[46:47], v[46:47], v[66:67], v[110:111] op_sel_hi:[1,0,1]
	v_pk_fma_f32 v[40:41], v[40:41], v[66:67], v[112:113] op_sel:[0,1,0]
	s_add_u32 s4, s4, 0x40000
	s_addc_u32 s5, s5, 0
	s_waitcnt vmcnt(20)
	v_cvt_pk_bf16_f32 v52, v48, v49
	v_cvt_pk_bf16_f32 v53, v44, v45
	v_cvt_pk_bf16_f32 v54, v46, v47
	v_cvt_pk_bf16_f32 v55, v40, v41
	global_store_dword v6, v52, s[4:5]
	global_store_dword v7, v53, s[4:5]
	global_store_dword v8, v54, s[4:5]
	global_store_dword v9, v55, s[4:5]
	v_lshlrev_b32_e32 v56, 16, v68
	v_and_b32_e32 v57, 0xffff0000, v68
	v_lshlrev_b32_e32 v58, 16, v69
	v_and_b32_e32 v59, 0xffff0000, v69
	v_lshlrev_b32_e32 v110, 16, v70
	v_and_b32_e32 v111, 0xffff0000, v70
	v_lshlrev_b32_e32 v112, 16, v71
	v_and_b32_e32 v113, 0xffff0000, v71
	v_pk_fma_f32 v[48:49], v[48:49], v[72:73], v[56:57] op_sel_hi:[1,0,1]
	v_pk_fma_f32 v[44:45], v[44:45], v[72:73], v[58:59] op_sel:[0,1,0]
	v_pk_fma_f32 v[46:47], v[46:47], v[74:75], v[110:111] op_sel_hi:[1,0,1]
	v_pk_fma_f32 v[40:41], v[40:41], v[74:75], v[112:113] op_sel:[0,1,0]
	s_add_u32 s4, s4, 0x40000
	s_addc_u32 s5, s5, 0
	s_branch .LBB0_574
